# staged pre-flush: the last three non-leader arrivers of an XCD each start an unwaited L2 write-back (was: only the second-to-last)
# speedup vs baseline: 1.0139x; 1.0006x over previous
.LBB0_856:
	s_or_b64 exec, exec, s[2:3]
	v_cvt_f32_u32_e32 v5, v3
	s_waitcnt vmcnt(0)
	v_readfirstlane_b32 s2, v4
	v_sub_u32_e32 v4, 0, v3
	v_rcp_iflag_f32_e32 v5, v5
	v_add_u32_e32 v6, s2, v0
	v_mul_f32_e32 v5, 0x4f7ffffe, v5
	v_cvt_u32_f32_e32 v5, v5
	v_mul_lo_u32 v0, v4, v5
	v_mul_hi_u32 v0, v5, v0
	v_add_u32_e32 v0, v5, v0
	v_mul_hi_u32 v0, v6, v0
	v_mul_lo_u32 v4, v0, v3
	v_sub_u32_e32 v4, v6, v4
	v_add_u32_e32 v5, 1, v0
	v_cmp_ge_u32_e32 vcc, v4, v3
	s_nop 1
	v_cndmask_b32_e32 v0, v0, v5, vcc
	v_sub_u32_e32 v5, v4, v3
	v_cndmask_b32_e32 v4, v4, v5, vcc
	v_add_u32_e32 v5, 1, v0
	v_cmp_ge_u32_e32 vcc, v4, v3
	v_add_u32_e32 v4, 1, v6
	s_nop 0
	v_cndmask_b32_e32 v0, v0, v5, vcc
	v_mul_lo_u32 v5, v3, v0
	v_add_u32_e32 v3, v5, v3
	v_cmp_ne_u32_e32 vcc, v4, v3
	v_sub_u32_e32 v6, v3, v4
	v_cmp_ge_u32_e64 s[6:7], 3, v6
	s_cbranch_vccz .Lxb_leader
	s_and_b64 s[6:7], s[6:7], exec
	s_cbranch_scc0 .Lxb_poll
	buffer_wbl2 sc1
	s_branch .Lxb_poll
